# v34 + nt on phase 0's f32 x-row loads (x -> bf16 + row rsqrt pass)
# speedup vs baseline: 1.0063x; 1.0063x over previous
.LBB0_40:
	s_or_b64 exec, exec, s[4:5]
	v_cmp_eq_u64_e64 s[4:5], 0, v[20:21]
	v_cmp_ne_u64_e64 s[6:7], 0, v[20:21]
	v_mov_b32_e32 v2, 0
	v_lshlrev_b32_e32 v36, 4, v34
	v_mov_b32_e32 v14, 0
	v_mov_b32_e32 v15, 0
	v_mov_b32_e32 v16, 0
	v_mov_b32_e32 v17, 0
	s_and_saveexec_b64 s[0:1], s[6:7]
	s_cbranch_execz .LBB0_42
	v_lshl_add_u64 v[4:5], v[20:21], 0, v[36:37]
	global_load_dwordx4 v[14:17], v[4:5], off nt
.LBB0_42:
	s_or_b64 exec, exec, s[0:1]
	v_cmp_eq_u64_e64 s[0:1], 0, v[44:45]
	v_cmp_ne_u64_e64 s[8:9], 0, v[44:45]
	v_mov_b32_e32 v3, 0
	v_mov_b32_e32 v4, 0
	v_mov_b32_e32 v5, 0
	s_and_saveexec_b64 s[18:19], s[8:9]
	s_cbranch_execz .LBB0_44
	v_lshl_add_u64 v[2:3], v[44:45], 0, v[36:37]
	global_load_dwordx4 v[2:5], v[2:3], off nt
.LBB0_44:
	s_or_b64 exec, exec, s[18:19]
	v_mov_b32_e32 v6, 0
	v_mov_b32_e32 v22, 0
	v_mov_b32_e32 v23, 0
	v_mov_b32_e32 v24, 0
	v_mov_b32_e32 v25, 0
	s_and_saveexec_b64 s[18:19], s[6:7]
	s_cbranch_execz .LBB0_46
	v_lshl_add_u64 v[8:9], v[20:21], 0, v[36:37]
	global_load_dwordx4 v[22:25], v[8:9], off offset:1024 nt
.LBB0_46:
	s_or_b64 exec, exec, s[18:19]
	v_mov_b32_e32 v7, 0
	v_mov_b32_e32 v8, 0
	v_mov_b32_e32 v9, 0
	s_and_saveexec_b64 s[18:19], s[8:9]
	s_cbranch_execz .LBB0_48
	v_lshl_add_u64 v[6:7], v[44:45], 0, v[36:37]
	global_load_dwordx4 v[6:9], v[6:7], off offset:1024 nt
.LBB0_48:
	s_or_b64 exec, exec, s[18:19]
	v_mov_b32_e32 v10, 0
	v_mov_b32_e32 v26, 0
	v_mov_b32_e32 v27, 0
	v_mov_b32_e32 v28, 0
	v_mov_b32_e32 v29, 0
	s_and_saveexec_b64 s[18:19], s[6:7]
	s_cbranch_execz .LBB0_50
	v_lshl_add_u64 v[12:13], v[20:21], 0, v[36:37]
	global_load_dwordx4 v[26:29], v[12:13], off offset:2048 nt
.LBB0_50:
	s_or_b64 exec, exec, s[18:19]
	v_mov_b32_e32 v11, 0
	v_mov_b32_e32 v12, 0
	v_mov_b32_e32 v13, 0
	s_and_saveexec_b64 s[18:19], s[8:9]
	s_cbranch_execz .LBB0_52
	v_lshl_add_u64 v[10:11], v[44:45], 0, v[36:37]
	global_load_dwordx4 v[10:13], v[10:11], off offset:2048 nt
.LBB0_52:
	s_or_b64 exec, exec, s[18:19]
	v_mov_b32_e32 v18, 0
	v_mov_b32_e32 v30, 0
	v_mov_b32_e32 v31, 0
	v_mov_b32_e32 v32, 0
	v_mov_b32_e32 v33, 0
	s_and_saveexec_b64 s[18:19], s[6:7]
	s_cbranch_execz .LBB0_54
	v_lshl_add_u64 v[20:21], v[20:21], 0, v[36:37]
	global_load_dwordx4 v[30:33], v[20:21], off offset:3072 nt
.LBB0_54:
	s_or_b64 exec, exec, s[18:19]
	v_mov_b32_e32 v19, 0
	v_mov_b32_e32 v20, 0
	v_mov_b32_e32 v21, 0
	s_and_saveexec_b64 s[6:7], s[8:9]
	s_cbranch_execz .LBB0_56
	v_lshl_add_u64 v[18:19], v[44:45], 0, v[36:37]
	global_load_dwordx4 v[18:21], v[18:19], off offset:3072 nt
